# P8 epilogue: rotary cos/sin rows loaded in two batches of eight per unit (ai=0 rows after the K loop, ai=1 rows after call 8) instead of 16 load-pair + vmcnt(0) round trips
# speedup vs baseline: 1.0087x; 1.0031x over previous
.LBB0_1234:
	ds_read_b128 v[150:153], v157
	ds_read_b128 v[160:163], v157 offset:1024
	ds_read_b128 v[164:167], v157 offset:2048
	ds_read_b128 v[168:171], v157 offset:3072
	ds_read_b128 v[172:175], v158
	ds_read_b128 v[176:179], v158 offset:1024
	ds_read_b128 v[180:183], v158 offset:2048
	ds_read_b128 v[184:187], v158 offset:3072
	s_add_u32 s30, s28, 0xfffc0080
	s_addc_u32 s31, s29, -1
	s_cmp_eq_u32 s46, 12
	s_cselect_b32 s35, s4, s31
	s_cselect_b32 s34, s5, s30
	s_cselect_b32 s31, s17, s27
	s_cselect_b32 s30, s19, s25
	v_lshl_add_u64 v[220:221], s[28:29], 0, v[142:143]
	s_add_i32 m0, s37, 0xc000
	ds_read_b128 v[188:191], v159
	ds_read_b128 v[192:195], v159 offset:1024
	ds_read_b128 v[196:199], v159 offset:2048
	ds_read_b128 v[200:203], v159 offset:3072
	ds_read_b128 v[204:207], v159 offset:4096
	ds_read_b128 v[208:211], v159 offset:5120
	ds_read_b128 v[212:215], v159 offset:6144
	ds_read_b128 v[216:219], v159 offset:7168
	global_load_lds_dwordx4 v[220:221], off
	v_lshl_add_u64 v[220:221], s[28:29], 0, v[144:145]
	s_add_i32 m0, s37, 0xe000
	s_nop 0
	global_load_lds_dwordx4 v[220:221], off
	s_waitcnt vmcnt(8)
	s_waitcnt lgkmcnt(0)
	s_barrier
	s_setprio 1
	s_waitcnt lgkmcnt(0)
	v_mfma_f32_16x16x32_bf16 v[124:127], v[150:153], v[188:191], v[124:127]
	v_mfma_f32_16x16x32_bf16 v[120:123], v[164:167], v[188:191], v[120:123]
	v_mfma_f32_16x16x32_bf16 v[108:111], v[150:153], v[196:199], v[108:111]
	v_mfma_f32_16x16x32_bf16 v[104:107], v[164:167], v[196:199], v[104:107]
	v_mfma_f32_16x16x32_bf16 v[92:95], v[150:153], v[204:207], v[92:95]
	v_mfma_f32_16x16x32_bf16 v[88:91], v[164:167], v[204:207], v[88:91]
	v_mfma_f32_16x16x32_bf16 v[76:79], v[150:153], v[212:215], v[76:79]
	v_mfma_f32_16x16x32_bf16 v[72:75], v[164:167], v[212:215], v[72:75]
	v_mfma_f32_16x16x32_bf16 v[124:127], v[160:163], v[192:195], v[124:127]
	v_mfma_f32_16x16x32_bf16 v[120:123], v[168:171], v[192:195], v[120:123]
	v_mfma_f32_16x16x32_bf16 v[108:111], v[160:163], v[200:203], v[108:111]
	v_mfma_f32_16x16x32_bf16 v[104:107], v[168:171], v[200:203], v[104:107]
	v_mfma_f32_16x16x32_bf16 v[92:95], v[160:163], v[208:211], v[92:95]
	v_mfma_f32_16x16x32_bf16 v[88:91], v[168:171], v[208:211], v[88:91]
	v_mfma_f32_16x16x32_bf16 v[76:79], v[160:163], v[216:219], v[76:79]
	v_mfma_f32_16x16x32_bf16 v[72:75], v[168:171], v[216:219], v[72:75]
	s_setprio 0
	s_setprio 1
	v_mfma_f32_16x16x32_bf16 v[116:119], v[172:175], v[188:191], v[116:119]
	v_mfma_f32_16x16x32_bf16 v[112:115], v[180:183], v[188:191], v[112:115]
	v_mfma_f32_16x16x32_bf16 v[100:103], v[172:175], v[196:199], v[100:103]
	v_mfma_f32_16x16x32_bf16 v[96:99], v[180:183], v[196:199], v[96:99]
	v_mfma_f32_16x16x32_bf16 v[84:87], v[172:175], v[204:207], v[84:87]
	v_mfma_f32_16x16x32_bf16 v[80:83], v[180:183], v[204:207], v[80:83]
	v_mfma_f32_16x16x32_bf16 v[68:71], v[172:175], v[212:215], v[68:71]
	v_mfma_f32_16x16x32_bf16 v[64:67], v[180:183], v[212:215], v[64:67]
	v_mfma_f32_16x16x32_bf16 v[116:119], v[176:179], v[192:195], v[116:119]
	v_mfma_f32_16x16x32_bf16 v[112:115], v[184:187], v[192:195], v[112:115]
	v_mfma_f32_16x16x32_bf16 v[100:103], v[176:179], v[200:203], v[100:103]
	v_mfma_f32_16x16x32_bf16 v[96:99], v[184:187], v[200:203], v[96:99]
	v_mfma_f32_16x16x32_bf16 v[84:87], v[176:179], v[208:211], v[84:87]
	v_mfma_f32_16x16x32_bf16 v[80:83], v[184:187], v[208:211], v[80:83]
	v_mfma_f32_16x16x32_bf16 v[68:71], v[176:179], v[216:219], v[68:71]
	v_mfma_f32_16x16x32_bf16 v[64:67], v[184:187], v[216:219], v[64:67]
	s_setprio 0
	s_barrier
	s_add_i32 s47, s44, s36
	v_lshl_add_u64 v[220:221], s[30:31], 0, v[130:131]
	s_mov_b32 m0, s47
	ds_read_b128 v[188:191], v159 offset:16384
	ds_read_b128 v[192:195], v159 offset:17408
	ds_read_b128 v[196:199], v159 offset:18432
	ds_read_b128 v[200:203], v159 offset:19456
	ds_read_b128 v[204:207], v159 offset:20480
	ds_read_b128 v[208:211], v159 offset:21504
	ds_read_b128 v[212:215], v159 offset:22528
	ds_read_b128 v[216:219], v159 offset:23552
	global_load_lds_dwordx4 v[220:221], off
	s_add_i32 m0, s47, 0x2000
	s_add_u32 s50, s30, 0x40000
	v_lshl_add_u64 v[222:223], s[30:31], 0, v[134:135]
	s_addc_u32 s51, s31, 0
	s_add_i32 s47, s45, s36
	global_load_lds_dwordx4 v[222:223], off
	v_lshl_add_u64 v[224:225], s[50:51], 0, v[130:131]
	s_mov_b32 m0, s47
	v_lshl_add_u64 v[228:229], s[34:35], 0, v[132:133]
	global_load_lds_dwordx4 v[224:225], off
	v_lshl_add_u64 v[224:225], s[50:51], 0, v[134:135]
	s_add_i32 m0, s47, 0x2000
	s_nop 0
	global_load_lds_dwordx4 v[224:225], off
	v_lshl_add_u64 v[224:225], s[34:35], 0, v[128:129]
	s_mov_b32 m0, s37
	s_nop 0
	global_load_lds_dwordx4 v[224:225], off
	s_mov_b32 m0, s38
	s_nop 0
	global_load_lds_dwordx4 v[228:229], off
	s_waitcnt vmcnt(8)
	s_waitcnt lgkmcnt(0)
	s_barrier
	s_setprio 1
	s_waitcnt lgkmcnt(0)
	v_mfma_f32_16x16x32_bf16 v[60:63], v[150:153], v[188:191], v[60:63]
	v_mfma_f32_16x16x32_bf16 v[56:59], v[164:167], v[188:191], v[56:59]
	v_mfma_f32_16x16x32_bf16 v[44:47], v[150:153], v[196:199], v[44:47]
	v_mfma_f32_16x16x32_bf16 v[40:43], v[164:167], v[196:199], v[40:43]
	v_mfma_f32_16x16x32_bf16 v[28:31], v[150:153], v[204:207], v[28:31]
	v_mfma_f32_16x16x32_bf16 v[24:27], v[164:167], v[204:207], v[24:27]
	v_mfma_f32_16x16x32_bf16 v[12:15], v[150:153], v[212:215], v[12:15]
	v_mfma_f32_16x16x32_bf16 v[8:11], v[164:167], v[212:215], v[8:11]
	v_mfma_f32_16x16x32_bf16 v[60:63], v[160:163], v[192:195], v[60:63]
	v_mfma_f32_16x16x32_bf16 v[56:59], v[168:171], v[192:195], v[56:59]
	v_mfma_f32_16x16x32_bf16 v[44:47], v[160:163], v[200:203], v[44:47]
	v_mfma_f32_16x16x32_bf16 v[40:43], v[168:171], v[200:203], v[40:43]
	v_mfma_f32_16x16x32_bf16 v[28:31], v[160:163], v[208:211], v[28:31]
	v_mfma_f32_16x16x32_bf16 v[24:27], v[168:171], v[208:211], v[24:27]
	v_mfma_f32_16x16x32_bf16 v[12:15], v[160:163], v[216:219], v[12:15]
	v_mfma_f32_16x16x32_bf16 v[8:11], v[168:171], v[216:219], v[8:11]
	s_setprio 0
	s_setprio 1
	v_mfma_f32_16x16x32_bf16 v[52:55], v[172:175], v[188:191], v[52:55]
	v_mfma_f32_16x16x32_bf16 v[48:51], v[180:183], v[188:191], v[48:51]
	v_mfma_f32_16x16x32_bf16 v[36:39], v[172:175], v[196:199], v[36:39]
	v_mfma_f32_16x16x32_bf16 v[32:35], v[180:183], v[196:199], v[32:35]
	v_mfma_f32_16x16x32_bf16 v[20:23], v[172:175], v[204:207], v[20:23]
	v_mfma_f32_16x16x32_bf16 v[16:19], v[180:183], v[204:207], v[16:19]
	v_mfma_f32_16x16x32_bf16 v[4:7], v[172:175], v[212:215], v[4:7]
	v_mfma_f32_16x16x32_bf16 v[0:3], v[180:183], v[212:215], v[0:3]
	v_mfma_f32_16x16x32_bf16 v[52:55], v[176:179], v[192:195], v[52:55]
	v_mfma_f32_16x16x32_bf16 v[48:51], v[184:187], v[192:195], v[48:51]
	v_mfma_f32_16x16x32_bf16 v[36:39], v[176:179], v[200:203], v[36:39]
	v_mfma_f32_16x16x32_bf16 v[32:35], v[184:187], v[200:203], v[32:35]
	v_mfma_f32_16x16x32_bf16 v[20:23], v[176:179], v[208:211], v[20:23]
	v_mfma_f32_16x16x32_bf16 v[16:19], v[184:187], v[208:211], v[16:19]
	v_mfma_f32_16x16x32_bf16 v[4:7], v[176:179], v[216:219], v[4:7]
	v_mfma_f32_16x16x32_bf16 v[0:3], v[184:187], v[216:219], v[0:3]
	s_setprio 0
	s_barrier
	s_add_i32 s47, 0, 0x18000
	v_add_u32_e32 v136, s47, v155
	s_add_i32 s49, 0, 0x1c000
	ds_read_b128 v[150:153], v136
	ds_read_b128 v[160:163], v136 offset:1024
	ds_read_b128 v[164:167], v136 offset:2048
	ds_read_b128 v[168:171], v136 offset:3072
	v_add_u32_e32 v136, s49, v155
	ds_read_b128 v[172:175], v136
	ds_read_b128 v[176:179], v136 offset:1024
	ds_read_b128 v[180:183], v136 offset:2048
	ds_read_b128 v[184:187], v136 offset:3072
	s_add_u32 s34, s34, 0x40000
	s_addc_u32 s35, s35, 0
	s_mov_b32 m0, s39
	v_lshl_add_u64 v[230:231], s[34:35], 0, v[128:129]
	ds_read_b128 v[188:191], v159 offset:32768
	ds_read_b128 v[192:195], v159 offset:33792
	ds_read_b128 v[196:199], v159 offset:34816
	ds_read_b128 v[200:203], v159 offset:35840
	ds_read_b128 v[204:207], v159 offset:36864
	ds_read_b128 v[208:211], v159 offset:37888
	ds_read_b128 v[212:215], v159 offset:38912
	ds_read_b128 v[216:219], v159 offset:39936
	global_load_lds_dwordx4 v[230:231], off
	v_lshl_add_u64 v[230:231], s[34:35], 0, v[132:133]
	s_mov_b32 m0, s40
	s_nop 0
	global_load_lds_dwordx4 v[230:231], off
	s_waitcnt vmcnt(8)
	s_waitcnt lgkmcnt(0)
	s_barrier
	s_setprio 1
	s_waitcnt lgkmcnt(0)
	v_mfma_f32_16x16x32_bf16 v[124:127], v[150:153], v[188:191], v[124:127]
	v_mfma_f32_16x16x32_bf16 v[120:123], v[164:167], v[188:191], v[120:123]
	v_mfma_f32_16x16x32_bf16 v[108:111], v[150:153], v[196:199], v[108:111]
	v_mfma_f32_16x16x32_bf16 v[104:107], v[164:167], v[196:199], v[104:107]
	v_mfma_f32_16x16x32_bf16 v[92:95], v[150:153], v[204:207], v[92:95]
	v_mfma_f32_16x16x32_bf16 v[88:91], v[164:167], v[204:207], v[88:91]
	v_mfma_f32_16x16x32_bf16 v[76:79], v[150:153], v[212:215], v[76:79]
	v_mfma_f32_16x16x32_bf16 v[72:75], v[164:167], v[212:215], v[72:75]
	v_mfma_f32_16x16x32_bf16 v[124:127], v[160:163], v[192:195], v[124:127]
	v_mfma_f32_16x16x32_bf16 v[120:123], v[168:171], v[192:195], v[120:123]
	v_mfma_f32_16x16x32_bf16 v[108:111], v[160:163], v[200:203], v[108:111]
	v_mfma_f32_16x16x32_bf16 v[104:107], v[168:171], v[200:203], v[104:107]
	v_mfma_f32_16x16x32_bf16 v[92:95], v[160:163], v[208:211], v[92:95]
	v_mfma_f32_16x16x32_bf16 v[88:91], v[168:171], v[208:211], v[88:91]
	v_mfma_f32_16x16x32_bf16 v[76:79], v[160:163], v[216:219], v[76:79]
	v_mfma_f32_16x16x32_bf16 v[72:75], v[168:171], v[216:219], v[72:75]
	s_setprio 0
	s_setprio 1
	v_mfma_f32_16x16x32_bf16 v[116:119], v[172:175], v[188:191], v[116:119]
	v_mfma_f32_16x16x32_bf16 v[112:115], v[180:183], v[188:191], v[112:115]
	v_mfma_f32_16x16x32_bf16 v[100:103], v[172:175], v[196:199], v[100:103]
	v_mfma_f32_16x16x32_bf16 v[96:99], v[180:183], v[196:199], v[96:99]
	v_mfma_f32_16x16x32_bf16 v[84:87], v[172:175], v[204:207], v[84:87]
	v_mfma_f32_16x16x32_bf16 v[80:83], v[180:183], v[204:207], v[80:83]
	v_mfma_f32_16x16x32_bf16 v[68:71], v[172:175], v[212:215], v[68:71]
	v_mfma_f32_16x16x32_bf16 v[64:67], v[180:183], v[212:215], v[64:67]
	v_mfma_f32_16x16x32_bf16 v[116:119], v[176:179], v[192:195], v[116:119]
	v_mfma_f32_16x16x32_bf16 v[112:115], v[184:187], v[192:195], v[112:115]
	v_mfma_f32_16x16x32_bf16 v[100:103], v[176:179], v[200:203], v[100:103]
	v_mfma_f32_16x16x32_bf16 v[96:99], v[184:187], v[200:203], v[96:99]
	v_mfma_f32_16x16x32_bf16 v[84:87], v[176:179], v[208:211], v[84:87]
	v_mfma_f32_16x16x32_bf16 v[80:83], v[184:187], v[208:211], v[80:83]
	v_mfma_f32_16x16x32_bf16 v[68:71], v[176:179], v[216:219], v[68:71]
	v_mfma_f32_16x16x32_bf16 v[64:67], v[184:187], v[216:219], v[64:67]
	s_setprio 0
	s_barrier
	s_add_i32 s34, s47, s36
	v_lshl_add_u64 v[220:221], v[220:221], 0, s[10:11]
	s_mov_b32 m0, s34
	ds_read_b128 v[188:191], v159 offset:49152
	ds_read_b128 v[192:195], v159 offset:50176
	ds_read_b128 v[196:199], v159 offset:51200
	ds_read_b128 v[200:203], v159 offset:52224
	ds_read_b128 v[204:207], v159 offset:53248
	ds_read_b128 v[208:211], v159 offset:54272
	ds_read_b128 v[212:215], v159 offset:55296
	ds_read_b128 v[216:219], v159 offset:56320
	global_load_lds_dwordx4 v[220:221], off
	s_add_i32 m0, s34, 0x2000
	s_add_u32 s30, s30, 0x40080
	v_lshl_add_u64 v[220:221], v[222:223], 0, s[10:11]
	s_addc_u32 s31, s31, 0
	s_add_i32 s34, s49, s36
	global_load_lds_dwordx4 v[220:221], off
	v_lshl_add_u64 v[220:221], s[30:31], 0, v[130:131]
	s_mov_b32 m0, s34
	s_nop 0
	global_load_lds_dwordx4 v[220:221], off
	v_lshl_add_u64 v[220:221], s[30:31], 0, v[134:135]
	s_add_i32 m0, s34, 0x2000
	s_nop 0
	global_load_lds_dwordx4 v[220:221], off
	v_lshl_add_u64 v[220:221], v[224:225], 0, s[10:11]
	s_mov_b32 m0, s42
	s_nop 0
	global_load_lds_dwordx4 v[220:221], off
	v_lshl_add_u64 v[220:221], v[228:229], 0, s[10:11]
	s_mov_b32 m0, s43
	s_nop 0
	global_load_lds_dwordx4 v[220:221], off
	s_waitcnt vmcnt(8)
	s_waitcnt lgkmcnt(0)
	s_barrier
	s_setprio 1
	s_waitcnt lgkmcnt(0)
	v_mfma_f32_16x16x32_bf16 v[60:63], v[150:153], v[188:191], v[60:63]
	v_mfma_f32_16x16x32_bf16 v[56:59], v[164:167], v[188:191], v[56:59]
	v_mfma_f32_16x16x32_bf16 v[44:47], v[150:153], v[196:199], v[44:47]
	v_mfma_f32_16x16x32_bf16 v[40:43], v[164:167], v[196:199], v[40:43]
	v_mfma_f32_16x16x32_bf16 v[28:31], v[150:153], v[204:207], v[28:31]
	v_mfma_f32_16x16x32_bf16 v[24:27], v[164:167], v[204:207], v[24:27]
	v_mfma_f32_16x16x32_bf16 v[12:15], v[150:153], v[212:215], v[12:15]
	v_mfma_f32_16x16x32_bf16 v[8:11], v[164:167], v[212:215], v[8:11]
	v_mfma_f32_16x16x32_bf16 v[60:63], v[160:163], v[192:195], v[60:63]
	v_mfma_f32_16x16x32_bf16 v[56:59], v[168:171], v[192:195], v[56:59]
	v_mfma_f32_16x16x32_bf16 v[44:47], v[160:163], v[200:203], v[44:47]
	v_mfma_f32_16x16x32_bf16 v[40:43], v[168:171], v[200:203], v[40:43]
	v_mfma_f32_16x16x32_bf16 v[28:31], v[160:163], v[208:211], v[28:31]
	v_mfma_f32_16x16x32_bf16 v[24:27], v[168:171], v[208:211], v[24:27]
	v_mfma_f32_16x16x32_bf16 v[12:15], v[160:163], v[216:219], v[12:15]
	v_mfma_f32_16x16x32_bf16 v[8:11], v[168:171], v[216:219], v[8:11]
	s_setprio 0
	s_setprio 1
	v_mfma_f32_16x16x32_bf16 v[52:55], v[172:175], v[188:191], v[52:55]
	v_mfma_f32_16x16x32_bf16 v[48:51], v[180:183], v[188:191], v[48:51]
	v_mfma_f32_16x16x32_bf16 v[36:39], v[172:175], v[196:199], v[36:39]
	v_mfma_f32_16x16x32_bf16 v[32:35], v[180:183], v[196:199], v[32:35]
	v_mfma_f32_16x16x32_bf16 v[20:23], v[172:175], v[204:207], v[20:23]
	v_mfma_f32_16x16x32_bf16 v[16:19], v[180:183], v[204:207], v[16:19]
	v_mfma_f32_16x16x32_bf16 v[4:7], v[172:175], v[212:215], v[4:7]
	v_mfma_f32_16x16x32_bf16 v[0:3], v[180:183], v[212:215], v[0:3]
	v_mfma_f32_16x16x32_bf16 v[52:55], v[176:179], v[192:195], v[52:55]
	v_mfma_f32_16x16x32_bf16 v[48:51], v[184:187], v[192:195], v[48:51]
	v_mfma_f32_16x16x32_bf16 v[36:39], v[176:179], v[200:203], v[36:39]
	v_mfma_f32_16x16x32_bf16 v[32:35], v[184:187], v[200:203], v[32:35]
	v_mfma_f32_16x16x32_bf16 v[20:23], v[176:179], v[208:211], v[20:23]
	v_mfma_f32_16x16x32_bf16 v[16:19], v[184:187], v[208:211], v[16:19]
	v_mfma_f32_16x16x32_bf16 v[4:7], v[176:179], v[216:219], v[4:7]
	v_mfma_f32_16x16x32_bf16 v[0:3], v[184:187], v[216:219], v[0:3]
	s_setprio 0
	s_barrier
	s_add_i32 s46, s46, 2
	s_add_u32 s28, s28, 0x100
	s_addc_u32 s29, s29, 0
	s_add_u32 s25, s25, 0x100
	s_addc_u32 s27, s27, 0
	s_cmp_gt_u32 s46, 13
	s_cbranch_scc0 .LBB0_1234
	s_bitcmp1_b32 s24, 2
	s_cbranch_scc1 .Lrope_skip1
	s_cmp_eq_u64 s[6:7], 0
	s_cbranch_scc1 .Lrope_skip1
	v_lshl_add_u32 v224, s26, 8, v154
	v_lshlrev_b32_e32 v224, 5, v224
	v_and_b32_e32 v224, 0x3ffe0, v224
	v_mov_b32_e32 v225, 0
	v_lshl_add_u64 v[216:217], v[138:139], 0, v[224:225]
	v_lshl_add_u64 v[218:219], v[140:141], 0, v[224:225]
	v_add_u32_e32 v224, 0x1000, v224
	v_lshl_add_u64 v[220:221], v[138:139], 0, v[224:225]
	v_lshl_add_u64 v[222:223], v[140:141], 0, v[224:225]
	global_load_dwordx4 v[184:187], v[216:217], off
	global_load_dwordx4 v[188:191], v[218:219], off
	global_load_dwordx4 v[192:195], v[216:217], off offset:512
	global_load_dwordx4 v[196:199], v[218:219], off offset:512
	global_load_dwordx4 v[200:203], v[216:217], off offset:1024
	global_load_dwordx4 v[204:207], v[218:219], off offset:1024
	global_load_dwordx4 v[208:211], v[216:217], off offset:1536
	global_load_dwordx4 v[212:215], v[218:219], off offset:1536
.Lrope_skip1:
	s_and_b64 vcc, exec, s[12:13]
	s_cbranch_vccz .LBB0_1237
	s_barrier
.LBB0_1237:
	s_lshl_b32 s17, s24, 8
	s_ashr_i32 s19, s24, 2
	s_cmp_eq_u32 s19, 2
	v_lshl_add_u32 v150, s26, 8, v154
	s_cselect_b64 vcc, -1, 0
	s_cmpk_lt_u32 s17, 0x400
	v_lshlrev_b32_e32 v136, 3, v150
	s_cselect_b64 s[4:5], -1, 0
	v_and_b32_e32 v136, 0xfe78, v136
	s_or_b64 s[4:5], vcc, s[4:5]
	s_and_b64 s[24:25], s[6:7], s[4:5]
	v_lshlrev_b32_e32 v152, 2, v136
	s_and_saveexec_b64 s[4:5], s[24:25]
	s_cbranch_execz .LBB0_1239
	v_mov_b32_e32 v153, v137
	s_waitcnt vmcnt(0)
	v_mov_b64_e32 v[160:161], v[184:185]
	v_mov_b64_e32 v[162:163], v[186:187]
	v_mov_b64_e32 v[164:165], v[188:189]
	v_mov_b64_e32 v[166:167], v[190:191]
	v_pk_mul_f32 v[168:169], v[124:125], v[160:161]
	v_pk_mul_f32 v[170:171], v[124:125], v[164:165] op_sel:[1,0] op_sel_hi:[0,0]
	v_pk_mul_f32 v[176:177], v[120:121], v[166:167] op_sel:[1,0] op_sel_hi:[0,0]
	v_mov_b32_e32 v164, v161
	v_mul_f32_e32 v136, v127, v165
	v_mul_f32_e32 v172, v127, v161
	v_pk_mul_f32 v[174:175], v[120:121], v[162:163]
	v_mov_b32_e32 v166, v163
	v_mul_f32_e32 v178, v123, v167
	v_mul_f32_e32 v180, v123, v163
	v_pk_fma_f32 v[124:125], v[124:125], v[160:161], v[170:171] op_sel_hi:[1,0,1]
	v_mov_b32_e32 v160, v165
	v_pk_fma_f32 v[120:121], v[120:121], v[162:163], v[176:177] op_sel_hi:[1,0,1]
	v_mov_b32_e32 v162, v167
	v_pk_fma_f32 v[182:183], v[126:127], v[164:165], v[136:137] op_sel_hi:[1,1,0] neg_lo:[0,0,1] neg_hi:[0,0,1]
	v_pk_fma_f32 v[164:165], v[122:123], v[166:167], v[178:179] op_sel_hi:[1,1,0] neg_lo:[0,0,1] neg_hi:[0,0,1]
	v_pk_fma_f32 v[160:161], v[126:127], v[160:161], v[172:173] op_sel_hi:[1,1,0]
	v_pk_fma_f32 v[162:163], v[122:123], v[162:163], v[180:181] op_sel_hi:[1,1,0]
	v_sub_f32_e32 v120, v174, v176
	v_sub_f32_e32 v124, v168, v170
	v_mov_b32_e32 v122, v164
	v_mov_b32_e32 v126, v182
	v_mov_b32_e32 v123, v162
	v_mov_b32_e32 v127, v160
.LBB0_1239:
	s_or_b64 exec, exec, s[4:5]
	s_mul_hi_i32 s4, s19, 0x8100000
	s_mul_i32 s19, s19, 0x8100000
	s_and_b32 s5, s17, 0x300
	v_ashrrev_i32_e32 v151, 31, v150
	v_pk_mul_f32 v[162:163], v[124:125], s[14:15] op_sel_hi:[1,0]
	v_pk_mul_f32 v[168:169], v[122:123], s[14:15] op_sel_hi:[1,0]
	s_add_u32 s26, s86, s19
	v_lshlrev_b64 v[160:161], 11, v[150:151]
	v_pk_mul_f32 v[166:167], v[120:121], s[14:15] op_sel_hi:[1,0]
	v_cndmask_b32_e32 v151, v122, v168, vcc
	v_cndmask_b32_e32 v122, v124, v162, vcc
	v_cndmask_b32_e32 v124, v125, v163, vcc
	v_or_b32_e32 v125, s5, v156
	s_addc_u32 s27, s87, s4
	v_pk_mul_f32 v[164:165], v[126:127], s[14:15] op_sel_hi:[1,0]
	v_cndmask_b32_e32 v166, v120, v166, vcc
	v_cndmask_b32_e32 v167, v121, v167, vcc
	v_lshl_add_u64 v[120:121], s[26:27], 0, v[160:161]
	v_lshlrev_b32_e32 v136, 1, v125
	v_cndmask_b32_e32 v153, v123, v169, vcc
	v_cndmask_b32_e32 v123, v126, v164, vcc
	v_lshl_add_u64 v[120:121], v[120:121], 0, v[136:137]
	v_cndmask_b32_e32 v126, v127, v165, vcc
	v_cvt_pk_bf16_f32 v122, v122, v124
	v_cvt_pk_bf16_f32 v123, v123, v126
	v_cvt_pk_bf16_f32 v124, v166, v167
	v_cvt_pk_bf16_f32 v125, v151, v153
	global_store_dwordx4 v[120:121], v[122:125], off
	s_and_saveexec_b64 s[4:5], s[24:25]
	s_cbranch_execz .LBB0_1241
	v_mov_b32_e32 v153, v137
	v_mov_b64_e32 v[122:123], v[184:185]
	v_mov_b64_e32 v[124:125], v[186:187]
	v_mov_b64_e32 v[160:161], v[188:189]
	v_mov_b64_e32 v[162:163], v[190:191]
	v_pk_mul_f32 v[126:127], v[116:117], v[122:123]
	v_pk_mul_f32 v[152:153], v[116:117], v[160:161] op_sel:[1,0] op_sel_hi:[0,0]
	v_pk_mul_f32 v[170:171], v[112:113], v[162:163] op_sel:[1,0] op_sel_hi:[0,0]
	v_mov_b32_e32 v160, v123
	v_mul_f32_e32 v164, v119, v161
	v_mul_f32_e32 v166, v119, v123
	v_pk_mul_f32 v[168:169], v[112:113], v[124:125]
	v_mov_b32_e32 v162, v125
	v_mul_f32_e32 v172, v115, v163
	v_mul_f32_e32 v174, v115, v125
	v_pk_fma_f32 v[116:117], v[116:117], v[122:123], v[152:153] op_sel_hi:[1,0,1]
	v_mov_b32_e32 v122, v161
	v_pk_fma_f32 v[112:113], v[112:113], v[124:125], v[170:171] op_sel_hi:[1,0,1]
	v_mov_b32_e32 v124, v163
	v_pk_fma_f32 v[164:165], v[118:119], v[160:161], v[164:165] op_sel_hi:[1,1,0] neg_lo:[0,0,1] neg_hi:[0,0,1]
	v_pk_fma_f32 v[160:161], v[114:115], v[162:163], v[172:173] op_sel_hi:[1,1,0] neg_lo:[0,0,1] neg_hi:[0,0,1]
	v_pk_fma_f32 v[122:123], v[118:119], v[122:123], v[166:167] op_sel_hi:[1,1,0]
	v_pk_fma_f32 v[124:125], v[114:115], v[124:125], v[174:175] op_sel_hi:[1,1,0]
	v_sub_f32_e32 v112, v168, v170
	v_sub_f32_e32 v116, v126, v152
	v_mov_b32_e32 v114, v160
	v_mov_b32_e32 v118, v164
	v_mov_b32_e32 v115, v124
	v_mov_b32_e32 v119, v122
.LBB0_1241:
	s_or_b64 exec, exec, s[4:5]
	v_pk_mul_f32 v[122:123], v[116:117], s[14:15] op_sel_hi:[1,0]
	v_pk_mul_f32 v[124:125], v[118:119], s[14:15] op_sel_hi:[1,0]
	v_pk_mul_f32 v[126:127], v[112:113], s[14:15] op_sel_hi:[1,0]
	v_pk_mul_f32 v[152:153], v[114:115], s[14:15] op_sel_hi:[1,0]
	s_nop 0
	v_cndmask_b32_e32 v151, v114, v152, vcc
	v_cndmask_b32_e32 v114, v112, v126, vcc
	v_cndmask_b32_e32 v126, v113, v127, vcc
	v_cndmask_b32_e32 v113, v118, v124, vcc
	v_cndmask_b32_e32 v112, v116, v122, vcc
	v_cndmask_b32_e32 v115, v115, v153, vcc
	v_cndmask_b32_e32 v118, v119, v125, vcc
	v_cndmask_b32_e32 v116, v117, v123, vcc
	v_cvt_pk_bf16_f32 v112, v112, v116
	v_cvt_pk_bf16_f32 v113, v113, v118
	v_cvt_pk_bf16_f32 v114, v114, v126
	v_cvt_pk_bf16_f32 v115, v151, v115
	global_store_dwordx4 v[120:121], v[112:115], off offset:256
	s_nop 1
	v_or_b32_e32 v114, 16, v150
	v_lshlrev_b32_e32 v112, 3, v114
	v_and_b32_e32 v112, 0xfef8, v112
	v_lshlrev_b32_e32 v112, 2, v112
	s_and_saveexec_b64 s[4:5], s[24:25]
	s_cbranch_execz .LBB0_1243
	v_mov_b32_e32 v113, v137
	v_mov_b64_e32 v[116:117], v[192:193]
	v_mov_b64_e32 v[118:119], v[194:195]
	v_mov_b64_e32 v[120:121], v[196:197]
	v_mov_b64_e32 v[122:123], v[198:199]
	v_pk_mul_f32 v[124:125], v[108:109], v[116:117]
	v_pk_mul_f32 v[126:127], v[108:109], v[120:121] op_sel:[1,0] op_sel_hi:[0,0]
	v_pk_mul_f32 v[164:165], v[104:105], v[122:123] op_sel:[1,0] op_sel_hi:[0,0]
	v_mov_b32_e32 v120, v117
	v_mul_f32_e32 v152, v111, v121
	v_mul_f32_e32 v160, v111, v117
	v_pk_mul_f32 v[162:163], v[104:105], v[118:119]
	v_mov_b32_e32 v122, v119
	v_mul_f32_e32 v166, v107, v123
	v_mul_f32_e32 v168, v107, v119
	v_pk_fma_f32 v[108:109], v[108:109], v[116:117], v[126:127] op_sel_hi:[1,0,1]
	v_mov_b32_e32 v116, v121
	v_pk_fma_f32 v[104:105], v[104:105], v[118:119], v[164:165] op_sel_hi:[1,0,1]
	v_mov_b32_e32 v118, v123
	v_pk_fma_f32 v[152:153], v[110:111], v[120:121], v[152:153] op_sel_hi:[1,1,0] neg_lo:[0,0,1] neg_hi:[0,0,1]
	v_pk_fma_f32 v[120:121], v[106:107], v[122:123], v[166:167] op_sel_hi:[1,1,0] neg_lo:[0,0,1] neg_hi:[0,0,1]
	v_pk_fma_f32 v[116:117], v[110:111], v[116:117], v[160:161] op_sel_hi:[1,1,0]
	v_pk_fma_f32 v[118:119], v[106:107], v[118:119], v[168:169] op_sel_hi:[1,1,0]
	v_sub_f32_e32 v104, v162, v164
	v_sub_f32_e32 v108, v124, v126
	v_mov_b32_e32 v106, v120
	v_mov_b32_e32 v110, v152
	v_mov_b32_e32 v107, v118
	v_mov_b32_e32 v111, v116
.LBB0_1243:
	s_or_b64 exec, exec, s[4:5]
	v_ashrrev_i32_e32 v115, 31, v114
	v_lshlrev_b64 v[114:115], 11, v[114:115]
	v_pk_mul_f32 v[120:121], v[104:105], s[14:15] op_sel_hi:[1,0]
	v_pk_mul_f32 v[116:117], v[108:109], s[14:15] op_sel_hi:[1,0]
	v_pk_mul_f32 v[118:119], v[110:111], s[14:15] op_sel_hi:[1,0]
	v_pk_mul_f32 v[122:123], v[106:107], s[14:15] op_sel_hi:[1,0]
	v_cndmask_b32_e32 v120, v104, v120, vcc
	v_cndmask_b32_e32 v121, v105, v121, vcc
	v_lshl_add_u64 v[104:105], s[26:27], 0, v[114:115]
	v_cndmask_b32_e32 v113, v106, v122, vcc
	v_cndmask_b32_e32 v122, v107, v123, vcc
	v_cndmask_b32_e32 v107, v110, v118, vcc
	v_cndmask_b32_e32 v106, v108, v116, vcc
	v_cndmask_b32_e32 v108, v109, v117, vcc
	v_lshl_add_u64 v[104:105], v[104:105], 0, v[136:137]
	v_cndmask_b32_e32 v110, v111, v119, vcc
	v_cvt_pk_bf16_f32 v106, v106, v108
	v_cvt_pk_bf16_f32 v107, v107, v110
	v_cvt_pk_bf16_f32 v108, v120, v121
	v_cvt_pk_bf16_f32 v109, v113, v122
	global_store_dwordx4 v[104:105], v[106:109], off
	s_and_saveexec_b64 s[4:5], s[24:25]
	s_cbranch_execz .LBB0_1245
	v_mov_b32_e32 v113, v137
	v_mov_b64_e32 v[106:107], v[192:193]
	v_mov_b64_e32 v[108:109], v[194:195]
	v_mov_b64_e32 v[110:111], v[196:197]
	v_mov_b64_e32 v[112:113], v[198:199]
	v_pk_mul_f32 v[114:115], v[100:101], v[106:107]
	v_pk_mul_f32 v[116:117], v[100:101], v[110:111] op_sel:[1,0] op_sel_hi:[0,0]
	v_pk_mul_f32 v[124:125], v[96:97], v[112:113] op_sel:[1,0] op_sel_hi:[0,0]
	v_mov_b32_e32 v110, v107
	v_mul_f32_e32 v118, v103, v111
	v_mul_f32_e32 v120, v103, v107
	v_pk_mul_f32 v[122:123], v[96:97], v[108:109]
	v_mov_b32_e32 v112, v109
	v_mul_f32_e32 v126, v99, v113
	v_mul_f32_e32 v152, v99, v109
	v_pk_fma_f32 v[100:101], v[100:101], v[106:107], v[116:117] op_sel_hi:[1,0,1]
	v_mov_b32_e32 v106, v111
	v_pk_fma_f32 v[96:97], v[96:97], v[108:109], v[124:125] op_sel_hi:[1,0,1]
	v_mov_b32_e32 v108, v113
	v_pk_fma_f32 v[118:119], v[102:103], v[110:111], v[118:119] op_sel_hi:[1,1,0] neg_lo:[0,0,1] neg_hi:[0,0,1]
	v_pk_fma_f32 v[110:111], v[98:99], v[112:113], v[126:127] op_sel_hi:[1,1,0] neg_lo:[0,0,1] neg_hi:[0,0,1]
	v_pk_fma_f32 v[106:107], v[102:103], v[106:107], v[120:121] op_sel_hi:[1,1,0]
	v_pk_fma_f32 v[108:109], v[98:99], v[108:109], v[152:153] op_sel_hi:[1,1,0]
	v_sub_f32_e32 v96, v122, v124
	v_sub_f32_e32 v100, v114, v116
	v_mov_b32_e32 v98, v110
	v_mov_b32_e32 v102, v118
	v_mov_b32_e32 v99, v108
	v_mov_b32_e32 v103, v106
.LBB0_1245:
	s_or_b64 exec, exec, s[4:5]
	v_pk_mul_f32 v[106:107], v[100:101], s[14:15] op_sel_hi:[1,0]
	v_pk_mul_f32 v[108:109], v[102:103], s[14:15] op_sel_hi:[1,0]
	v_pk_mul_f32 v[110:111], v[96:97], s[14:15] op_sel_hi:[1,0]
	v_pk_mul_f32 v[112:113], v[98:99], s[14:15] op_sel_hi:[1,0]
	s_nop 0
	v_cndmask_b32_e32 v112, v98, v112, vcc
	v_cndmask_b32_e32 v98, v96, v110, vcc
	v_cndmask_b32_e32 v110, v97, v111, vcc
	v_cndmask_b32_e32 v97, v102, v108, vcc
	v_cndmask_b32_e32 v96, v100, v106, vcc
	v_cndmask_b32_e32 v99, v99, v113, vcc
	v_cndmask_b32_e32 v102, v103, v109, vcc
	v_cndmask_b32_e32 v100, v101, v107, vcc
	v_cvt_pk_bf16_f32 v96, v96, v100
	v_cvt_pk_bf16_f32 v97, v97, v102
	v_cvt_pk_bf16_f32 v98, v98, v110
	v_cvt_pk_bf16_f32 v99, v112, v99
	global_store_dwordx4 v[104:105], v[96:99], off offset:256
	s_nop 1
	v_or_b32_e32 v98, 32, v150
	v_lshlrev_b32_e32 v96, 3, v98
	v_and_b32_e32 v96, 0xff78, v96
	v_lshlrev_b32_e32 v96, 2, v96
	s_and_saveexec_b64 s[4:5], s[24:25]
	s_cbranch_execz .LBB0_1247
	v_mov_b32_e32 v97, v137
	v_mov_b64_e32 v[100:101], v[200:201]
	v_mov_b64_e32 v[102:103], v[202:203]
	v_mov_b64_e32 v[104:105], v[204:205]
	v_mov_b64_e32 v[106:107], v[206:207]
	v_pk_mul_f32 v[108:109], v[92:93], v[100:101]
	v_pk_mul_f32 v[110:111], v[92:93], v[104:105] op_sel:[1,0] op_sel_hi:[0,0]
	v_pk_mul_f32 v[118:119], v[88:89], v[106:107] op_sel:[1,0] op_sel_hi:[0,0]
	v_mov_b32_e32 v104, v101
	v_mul_f32_e32 v112, v95, v105
	v_mul_f32_e32 v114, v95, v101
	v_pk_mul_f32 v[116:117], v[88:89], v[102:103]
	v_mov_b32_e32 v106, v103
	v_mul_f32_e32 v120, v91, v107
	v_mul_f32_e32 v122, v91, v103
	v_pk_fma_f32 v[92:93], v[92:93], v[100:101], v[110:111] op_sel_hi:[1,0,1]
	v_mov_b32_e32 v100, v105
	v_pk_fma_f32 v[88:89], v[88:89], v[102:103], v[118:119] op_sel_hi:[1,0,1]
	v_mov_b32_e32 v102, v107
	v_pk_fma_f32 v[112:113], v[94:95], v[104:105], v[112:113] op_sel_hi:[1,1,0] neg_lo:[0,0,1] neg_hi:[0,0,1]
	v_pk_fma_f32 v[104:105], v[90:91], v[106:107], v[120:121] op_sel_hi:[1,1,0] neg_lo:[0,0,1] neg_hi:[0,0,1]
	v_pk_fma_f32 v[100:101], v[94:95], v[100:101], v[114:115] op_sel_hi:[1,1,0]
	v_pk_fma_f32 v[102:103], v[90:91], v[102:103], v[122:123] op_sel_hi:[1,1,0]
	v_sub_f32_e32 v88, v116, v118
	v_sub_f32_e32 v92, v108, v110
	v_mov_b32_e32 v90, v104
	v_mov_b32_e32 v94, v112
	v_mov_b32_e32 v91, v102
	v_mov_b32_e32 v95, v100
.LBB0_1247:
	s_or_b64 exec, exec, s[4:5]
	v_ashrrev_i32_e32 v99, 31, v98
	v_lshlrev_b64 v[98:99], 11, v[98:99]
	v_pk_mul_f32 v[104:105], v[88:89], s[14:15] op_sel_hi:[1,0]
	v_pk_mul_f32 v[100:101], v[92:93], s[14:15] op_sel_hi:[1,0]
	v_pk_mul_f32 v[102:103], v[94:95], s[14:15] op_sel_hi:[1,0]
	v_pk_mul_f32 v[106:107], v[90:91], s[14:15] op_sel_hi:[1,0]
	v_cndmask_b32_e32 v104, v88, v104, vcc
	v_cndmask_b32_e32 v105, v89, v105, vcc
	v_lshl_add_u64 v[88:89], s[26:27], 0, v[98:99]
	v_cndmask_b32_e32 v97, v90, v106, vcc
	v_cndmask_b32_e32 v106, v91, v107, vcc
	v_cndmask_b32_e32 v91, v94, v102, vcc
	v_cndmask_b32_e32 v90, v92, v100, vcc
	v_cndmask_b32_e32 v92, v93, v101, vcc
	v_lshl_add_u64 v[88:89], v[88:89], 0, v[136:137]
	v_cndmask_b32_e32 v94, v95, v103, vcc
	v_cvt_pk_bf16_f32 v90, v90, v92
	v_cvt_pk_bf16_f32 v91, v91, v94
	v_cvt_pk_bf16_f32 v92, v104, v105
	v_cvt_pk_bf16_f32 v93, v97, v106
	global_store_dwordx4 v[88:89], v[90:93], off
	s_and_saveexec_b64 s[4:5], s[24:25]
	s_cbranch_execz .LBB0_1249
	v_mov_b32_e32 v97, v137
	v_mov_b64_e32 v[90:91], v[200:201]
	v_mov_b64_e32 v[92:93], v[202:203]
	v_mov_b64_e32 v[94:95], v[204:205]
	v_mov_b64_e32 v[96:97], v[206:207]
	v_pk_mul_f32 v[98:99], v[84:85], v[90:91]
	v_pk_mul_f32 v[100:101], v[84:85], v[94:95] op_sel:[1,0] op_sel_hi:[0,0]
	v_pk_mul_f32 v[108:109], v[80:81], v[96:97] op_sel:[1,0] op_sel_hi:[0,0]
	v_mov_b32_e32 v94, v91
	v_mul_f32_e32 v102, v87, v95
	v_mul_f32_e32 v104, v87, v91
	v_pk_mul_f32 v[106:107], v[80:81], v[92:93]
	v_mov_b32_e32 v96, v93
	v_mul_f32_e32 v110, v83, v97
	v_mul_f32_e32 v112, v83, v93
	v_pk_fma_f32 v[84:85], v[84:85], v[90:91], v[100:101] op_sel_hi:[1,0,1]
	v_mov_b32_e32 v90, v95
	v_pk_fma_f32 v[80:81], v[80:81], v[92:93], v[108:109] op_sel_hi:[1,0,1]
	v_mov_b32_e32 v92, v97
	v_pk_fma_f32 v[102:103], v[86:87], v[94:95], v[102:103] op_sel_hi:[1,1,0] neg_lo:[0,0,1] neg_hi:[0,0,1]
	v_pk_fma_f32 v[94:95], v[82:83], v[96:97], v[110:111] op_sel_hi:[1,1,0] neg_lo:[0,0,1] neg_hi:[0,0,1]
	v_pk_fma_f32 v[90:91], v[86:87], v[90:91], v[104:105] op_sel_hi:[1,1,0]
	v_pk_fma_f32 v[92:93], v[82:83], v[92:93], v[112:113] op_sel_hi:[1,1,0]
	v_sub_f32_e32 v80, v106, v108
	v_sub_f32_e32 v84, v98, v100
	v_mov_b32_e32 v82, v94
	v_mov_b32_e32 v86, v102
	v_mov_b32_e32 v83, v92
	v_mov_b32_e32 v87, v90
.LBB0_1249:
	s_or_b64 exec, exec, s[4:5]
	v_pk_mul_f32 v[90:91], v[84:85], s[14:15] op_sel_hi:[1,0]
	v_pk_mul_f32 v[92:93], v[86:87], s[14:15] op_sel_hi:[1,0]
	v_pk_mul_f32 v[94:95], v[80:81], s[14:15] op_sel_hi:[1,0]
	v_pk_mul_f32 v[96:97], v[82:83], s[14:15] op_sel_hi:[1,0]
	s_nop 0
	v_cndmask_b32_e32 v96, v82, v96, vcc
	v_cndmask_b32_e32 v82, v80, v94, vcc
	v_cndmask_b32_e32 v94, v81, v95, vcc
	v_cndmask_b32_e32 v81, v86, v92, vcc
	v_cndmask_b32_e32 v80, v84, v90, vcc
	v_cndmask_b32_e32 v83, v83, v97, vcc
	v_cndmask_b32_e32 v86, v87, v93, vcc
	v_cndmask_b32_e32 v84, v85, v91, vcc
	v_cvt_pk_bf16_f32 v80, v80, v84
	v_cvt_pk_bf16_f32 v81, v81, v86
	v_cvt_pk_bf16_f32 v82, v82, v94
	v_cvt_pk_bf16_f32 v83, v96, v83
	global_store_dwordx4 v[88:89], v[80:83], off offset:256
	s_nop 1
	v_or_b32_e32 v82, 48, v150
	v_lshlrev_b32_e32 v80, 3, v82
	v_and_b32_e32 v80, 0xfff8, v80
	v_lshlrev_b32_e32 v80, 2, v80
	s_and_saveexec_b64 s[4:5], s[24:25]
	s_cbranch_execz .LBB0_1251
	v_mov_b32_e32 v81, v137
	v_mov_b64_e32 v[84:85], v[208:209]
	v_mov_b64_e32 v[86:87], v[210:211]
	v_mov_b64_e32 v[88:89], v[212:213]
	v_mov_b64_e32 v[90:91], v[214:215]
	v_pk_mul_f32 v[92:93], v[76:77], v[84:85]
	v_pk_mul_f32 v[94:95], v[76:77], v[88:89] op_sel:[1,0] op_sel_hi:[0,0]
	v_pk_mul_f32 v[102:103], v[72:73], v[90:91] op_sel:[1,0] op_sel_hi:[0,0]
	v_mov_b32_e32 v88, v85
	v_mul_f32_e32 v96, v79, v89
	v_mul_f32_e32 v98, v79, v85
	v_pk_mul_f32 v[100:101], v[72:73], v[86:87]
	v_mov_b32_e32 v90, v87
	v_mul_f32_e32 v104, v75, v91
	v_mul_f32_e32 v106, v75, v87
	v_pk_fma_f32 v[76:77], v[76:77], v[84:85], v[94:95] op_sel_hi:[1,0,1]
	v_mov_b32_e32 v84, v89
	v_pk_fma_f32 v[72:73], v[72:73], v[86:87], v[102:103] op_sel_hi:[1,0,1]
	v_mov_b32_e32 v86, v91
	v_pk_fma_f32 v[96:97], v[78:79], v[88:89], v[96:97] op_sel_hi:[1,1,0] neg_lo:[0,0,1] neg_hi:[0,0,1]
	v_pk_fma_f32 v[88:89], v[74:75], v[90:91], v[104:105] op_sel_hi:[1,1,0] neg_lo:[0,0,1] neg_hi:[0,0,1]
	v_pk_fma_f32 v[84:85], v[78:79], v[84:85], v[98:99] op_sel_hi:[1,1,0]
	v_pk_fma_f32 v[86:87], v[74:75], v[86:87], v[106:107] op_sel_hi:[1,1,0]
	v_sub_f32_e32 v72, v100, v102
	v_sub_f32_e32 v76, v92, v94
	v_mov_b32_e32 v74, v88
	v_mov_b32_e32 v78, v96
	v_mov_b32_e32 v75, v86
	v_mov_b32_e32 v79, v84
.LBB0_1251:
	s_or_b64 exec, exec, s[4:5]
	v_ashrrev_i32_e32 v83, 31, v82
	v_lshlrev_b64 v[82:83], 11, v[82:83]
	v_pk_mul_f32 v[88:89], v[72:73], s[14:15] op_sel_hi:[1,0]
	v_pk_mul_f32 v[84:85], v[76:77], s[14:15] op_sel_hi:[1,0]
	v_pk_mul_f32 v[86:87], v[78:79], s[14:15] op_sel_hi:[1,0]
	v_pk_mul_f32 v[90:91], v[74:75], s[14:15] op_sel_hi:[1,0]
	v_cndmask_b32_e32 v88, v72, v88, vcc
	v_cndmask_b32_e32 v89, v73, v89, vcc
	v_lshl_add_u64 v[72:73], s[26:27], 0, v[82:83]
	v_cndmask_b32_e32 v81, v74, v90, vcc
	v_cndmask_b32_e32 v90, v75, v91, vcc
	v_cndmask_b32_e32 v75, v78, v86, vcc
	v_cndmask_b32_e32 v74, v76, v84, vcc
	v_cndmask_b32_e32 v76, v77, v85, vcc
	v_lshl_add_u64 v[72:73], v[72:73], 0, v[136:137]
	v_cndmask_b32_e32 v78, v79, v87, vcc
	v_cvt_pk_bf16_f32 v74, v74, v76
	v_cvt_pk_bf16_f32 v75, v75, v78
	v_cvt_pk_bf16_f32 v76, v88, v89
	v_cvt_pk_bf16_f32 v77, v81, v90
	global_store_dwordx4 v[72:73], v[74:77], off
	s_and_saveexec_b64 s[4:5], s[24:25]
	s_cbranch_execz .LBB0_1253
	v_mov_b32_e32 v81, v137
	v_mov_b64_e32 v[74:75], v[208:209]
	v_mov_b64_e32 v[76:77], v[210:211]
	v_mov_b64_e32 v[78:79], v[212:213]
	v_mov_b64_e32 v[80:81], v[214:215]
	v_pk_mul_f32 v[82:83], v[68:69], v[74:75]
	v_pk_mul_f32 v[84:85], v[68:69], v[78:79] op_sel:[1,0] op_sel_hi:[0,0]
	v_pk_mul_f32 v[92:93], v[64:65], v[80:81] op_sel:[1,0] op_sel_hi:[0,0]
	v_mov_b32_e32 v78, v75
	v_mul_f32_e32 v86, v71, v79
	v_mul_f32_e32 v88, v71, v75
	v_pk_mul_f32 v[90:91], v[64:65], v[76:77]
	v_mov_b32_e32 v80, v77
	v_mul_f32_e32 v94, v67, v81
	v_mul_f32_e32 v96, v67, v77
	v_pk_fma_f32 v[68:69], v[68:69], v[74:75], v[84:85] op_sel_hi:[1,0,1]
	v_mov_b32_e32 v74, v79
	v_pk_fma_f32 v[64:65], v[64:65], v[76:77], v[92:93] op_sel_hi:[1,0,1]
	v_mov_b32_e32 v76, v81
	v_pk_fma_f32 v[86:87], v[70:71], v[78:79], v[86:87] op_sel_hi:[1,1,0] neg_lo:[0,0,1] neg_hi:[0,0,1]
	v_pk_fma_f32 v[78:79], v[66:67], v[80:81], v[94:95] op_sel_hi:[1,1,0] neg_lo:[0,0,1] neg_hi:[0,0,1]
	v_pk_fma_f32 v[74:75], v[70:71], v[74:75], v[88:89] op_sel_hi:[1,1,0]
	v_pk_fma_f32 v[76:77], v[66:67], v[76:77], v[96:97] op_sel_hi:[1,1,0]
	v_sub_f32_e32 v64, v90, v92
	v_sub_f32_e32 v68, v82, v84
	v_mov_b32_e32 v66, v78
	v_mov_b32_e32 v70, v86
	v_mov_b32_e32 v67, v76
	v_mov_b32_e32 v71, v74
.LBB0_1253:
	s_or_b64 exec, exec, s[4:5]
	s_cmp_eq_u64 s[24:25], 0
	s_cbranch_scc1 .Lrope_skip2
	global_load_dwordx4 v[184:187], v[220:221], off
	global_load_dwordx4 v[188:191], v[222:223], off
	global_load_dwordx4 v[192:195], v[220:221], off offset:512
	global_load_dwordx4 v[196:199], v[222:223], off offset:512
	global_load_dwordx4 v[200:203], v[220:221], off offset:1024
	global_load_dwordx4 v[204:207], v[222:223], off offset:1024
	global_load_dwordx4 v[208:211], v[220:221], off offset:1536
	global_load_dwordx4 v[212:215], v[222:223], off offset:1536
.Lrope_skip2:
	v_pk_mul_f32 v[74:75], v[68:69], s[14:15] op_sel_hi:[1,0]
	v_pk_mul_f32 v[76:77], v[70:71], s[14:15] op_sel_hi:[1,0]
	v_pk_mul_f32 v[78:79], v[64:65], s[14:15] op_sel_hi:[1,0]
	v_pk_mul_f32 v[80:81], v[66:67], s[14:15] op_sel_hi:[1,0]
	s_nop 0
	v_cndmask_b32_e32 v80, v66, v80, vcc
	v_cndmask_b32_e32 v66, v64, v78, vcc
	v_cndmask_b32_e32 v78, v65, v79, vcc
	v_cndmask_b32_e32 v65, v70, v76, vcc
	v_cndmask_b32_e32 v64, v68, v74, vcc
	v_cndmask_b32_e32 v67, v67, v81, vcc
	v_cndmask_b32_e32 v70, v71, v77, vcc
	v_cndmask_b32_e32 v68, v69, v75, vcc
	v_cvt_pk_bf16_f32 v64, v64, v68
	v_cvt_pk_bf16_f32 v65, v65, v70
	v_cvt_pk_bf16_f32 v66, v66, v78
	v_cvt_pk_bf16_f32 v67, v80, v67
	global_store_dwordx4 v[72:73], v[64:67], off offset:256
	s_nop 1
	v_add_u32_e32 v66, 0x80, v150
	v_lshlrev_b32_e32 v64, 3, v66
	v_and_b32_e32 v64, 0xfe78, v64
	v_lshlrev_b32_e32 v64, 2, v64
	s_and_saveexec_b64 s[4:5], s[24:25]
	s_cbranch_execz .LBB0_1255
	v_mov_b32_e32 v65, v137
	s_waitcnt vmcnt(1)
	v_mov_b64_e32 v[68:69], v[184:185]
	v_mov_b64_e32 v[70:71], v[186:187]
	v_mov_b64_e32 v[72:73], v[188:189]
	v_mov_b64_e32 v[74:75], v[190:191]
	v_pk_mul_f32 v[76:77], v[60:61], v[68:69]
	v_pk_mul_f32 v[78:79], v[60:61], v[72:73] op_sel:[1,0] op_sel_hi:[0,0]
	v_pk_mul_f32 v[86:87], v[56:57], v[74:75] op_sel:[1,0] op_sel_hi:[0,0]
	v_mov_b32_e32 v72, v69
	v_mul_f32_e32 v80, v63, v73
	v_mul_f32_e32 v82, v63, v69
	v_pk_mul_f32 v[84:85], v[56:57], v[70:71]
	v_mov_b32_e32 v74, v71
	v_mul_f32_e32 v88, v59, v75
	v_mul_f32_e32 v90, v59, v71
	v_pk_fma_f32 v[60:61], v[60:61], v[68:69], v[78:79] op_sel_hi:[1,0,1]
	v_mov_b32_e32 v68, v73
	v_pk_fma_f32 v[56:57], v[56:57], v[70:71], v[86:87] op_sel_hi:[1,0,1]
	v_mov_b32_e32 v70, v75
	v_pk_fma_f32 v[80:81], v[62:63], v[72:73], v[80:81] op_sel_hi:[1,1,0] neg_lo:[0,0,1] neg_hi:[0,0,1]
	v_pk_fma_f32 v[72:73], v[58:59], v[74:75], v[88:89] op_sel_hi:[1,1,0] neg_lo:[0,0,1] neg_hi:[0,0,1]
	v_pk_fma_f32 v[68:69], v[62:63], v[68:69], v[82:83] op_sel_hi:[1,1,0]
	v_pk_fma_f32 v[70:71], v[58:59], v[70:71], v[90:91] op_sel_hi:[1,1,0]
	v_sub_f32_e32 v56, v84, v86
	v_sub_f32_e32 v60, v76, v78
	v_mov_b32_e32 v58, v72
	v_mov_b32_e32 v62, v80
	v_mov_b32_e32 v59, v70
	v_mov_b32_e32 v63, v68
.LBB0_1255:
	s_or_b64 exec, exec, s[4:5]
	v_ashrrev_i32_e32 v67, 31, v66
	v_lshlrev_b64 v[66:67], 11, v[66:67]
	v_pk_mul_f32 v[72:73], v[56:57], s[14:15] op_sel_hi:[1,0]
	v_pk_mul_f32 v[68:69], v[60:61], s[14:15] op_sel_hi:[1,0]
	v_pk_mul_f32 v[70:71], v[62:63], s[14:15] op_sel_hi:[1,0]
	v_pk_mul_f32 v[74:75], v[58:59], s[14:15] op_sel_hi:[1,0]
	v_cndmask_b32_e32 v72, v56, v72, vcc
	v_cndmask_b32_e32 v73, v57, v73, vcc
	v_lshl_add_u64 v[56:57], s[26:27], 0, v[66:67]
	v_cndmask_b32_e32 v65, v58, v74, vcc
	v_cndmask_b32_e32 v74, v59, v75, vcc
	v_cndmask_b32_e32 v59, v62, v70, vcc
	v_cndmask_b32_e32 v58, v60, v68, vcc
	v_cndmask_b32_e32 v60, v61, v69, vcc
	v_lshl_add_u64 v[56:57], v[56:57], 0, v[136:137]
	v_cndmask_b32_e32 v62, v63, v71, vcc
	v_cvt_pk_bf16_f32 v58, v58, v60
	v_cvt_pk_bf16_f32 v59, v59, v62
	v_cvt_pk_bf16_f32 v60, v72, v73
	v_cvt_pk_bf16_f32 v61, v65, v74
	global_store_dwordx4 v[56:57], v[58:61], off
	s_and_saveexec_b64 s[4:5], s[24:25]
	s_cbranch_execz .LBB0_1257
	v_mov_b32_e32 v65, v137
	v_mov_b64_e32 v[58:59], v[184:185]
	v_mov_b64_e32 v[60:61], v[186:187]
	v_mov_b64_e32 v[62:63], v[188:189]
	v_mov_b64_e32 v[64:65], v[190:191]
	v_pk_mul_f32 v[66:67], v[52:53], v[58:59]
	v_pk_mul_f32 v[68:69], v[52:53], v[62:63] op_sel:[1,0] op_sel_hi:[0,0]
	v_pk_mul_f32 v[76:77], v[48:49], v[64:65] op_sel:[1,0] op_sel_hi:[0,0]
	v_mov_b32_e32 v62, v59
	v_mul_f32_e32 v70, v55, v63
	v_mul_f32_e32 v72, v55, v59
	v_pk_mul_f32 v[74:75], v[48:49], v[60:61]
	v_mov_b32_e32 v64, v61
	v_mul_f32_e32 v78, v51, v65
	v_mul_f32_e32 v80, v51, v61
	v_pk_fma_f32 v[52:53], v[52:53], v[58:59], v[68:69] op_sel_hi:[1,0,1]
	v_mov_b32_e32 v58, v63
	v_pk_fma_f32 v[48:49], v[48:49], v[60:61], v[76:77] op_sel_hi:[1,0,1]
	v_mov_b32_e32 v60, v65
	v_pk_fma_f32 v[70:71], v[54:55], v[62:63], v[70:71] op_sel_hi:[1,1,0] neg_lo:[0,0,1] neg_hi:[0,0,1]
	v_pk_fma_f32 v[62:63], v[50:51], v[64:65], v[78:79] op_sel_hi:[1,1,0] neg_lo:[0,0,1] neg_hi:[0,0,1]
	v_pk_fma_f32 v[58:59], v[54:55], v[58:59], v[72:73] op_sel_hi:[1,1,0]
	v_pk_fma_f32 v[60:61], v[50:51], v[60:61], v[80:81] op_sel_hi:[1,1,0]
	v_sub_f32_e32 v48, v74, v76
	v_sub_f32_e32 v52, v66, v68
	v_mov_b32_e32 v50, v62
	v_mov_b32_e32 v54, v70
	v_mov_b32_e32 v51, v60
	v_mov_b32_e32 v55, v58
.LBB0_1257:
	s_or_b64 exec, exec, s[4:5]
	v_pk_mul_f32 v[58:59], v[52:53], s[14:15] op_sel_hi:[1,0]
	v_pk_mul_f32 v[60:61], v[54:55], s[14:15] op_sel_hi:[1,0]
	v_pk_mul_f32 v[62:63], v[48:49], s[14:15] op_sel_hi:[1,0]
	v_pk_mul_f32 v[64:65], v[50:51], s[14:15] op_sel_hi:[1,0]
	s_nop 0
	v_cndmask_b32_e32 v64, v50, v64, vcc
	v_cndmask_b32_e32 v50, v48, v62, vcc
	v_cndmask_b32_e32 v62, v49, v63, vcc
	v_cndmask_b32_e32 v49, v54, v60, vcc
	v_cndmask_b32_e32 v48, v52, v58, vcc
	v_cndmask_b32_e32 v51, v51, v65, vcc
	v_cndmask_b32_e32 v54, v55, v61, vcc
	v_cndmask_b32_e32 v52, v53, v59, vcc
	v_cvt_pk_bf16_f32 v48, v48, v52
	v_cvt_pk_bf16_f32 v49, v49, v54
	v_cvt_pk_bf16_f32 v50, v50, v62
	v_cvt_pk_bf16_f32 v51, v64, v51
	global_store_dwordx4 v[56:57], v[48:51], off offset:256
	s_nop 1
	v_add_u32_e32 v50, 0x90, v150
	v_lshlrev_b32_e32 v48, 3, v50
	v_and_b32_e32 v48, 0xfef8, v48
	v_lshlrev_b32_e32 v48, 2, v48
	s_and_saveexec_b64 s[4:5], s[24:25]
	s_cbranch_execz .LBB0_1259
	v_mov_b32_e32 v49, v137
	v_mov_b64_e32 v[52:53], v[192:193]
	v_mov_b64_e32 v[54:55], v[194:195]
	v_mov_b64_e32 v[56:57], v[196:197]
	v_mov_b64_e32 v[58:59], v[198:199]
	v_pk_mul_f32 v[60:61], v[44:45], v[52:53]
	v_pk_mul_f32 v[62:63], v[44:45], v[56:57] op_sel:[1,0] op_sel_hi:[0,0]
	v_pk_mul_f32 v[70:71], v[40:41], v[58:59] op_sel:[1,0] op_sel_hi:[0,0]
	v_mov_b32_e32 v56, v53
	v_mul_f32_e32 v64, v47, v57
	v_mul_f32_e32 v66, v47, v53
	v_pk_mul_f32 v[68:69], v[40:41], v[54:55]
	v_mov_b32_e32 v58, v55
	v_mul_f32_e32 v72, v43, v59
	v_mul_f32_e32 v74, v43, v55
	v_pk_fma_f32 v[44:45], v[44:45], v[52:53], v[62:63] op_sel_hi:[1,0,1]
	v_mov_b32_e32 v52, v57
	v_pk_fma_f32 v[40:41], v[40:41], v[54:55], v[70:71] op_sel_hi:[1,0,1]
	v_mov_b32_e32 v54, v59
	v_pk_fma_f32 v[64:65], v[46:47], v[56:57], v[64:65] op_sel_hi:[1,1,0] neg_lo:[0,0,1] neg_hi:[0,0,1]
	v_pk_fma_f32 v[56:57], v[42:43], v[58:59], v[72:73] op_sel_hi:[1,1,0] neg_lo:[0,0,1] neg_hi:[0,0,1]
	v_pk_fma_f32 v[52:53], v[46:47], v[52:53], v[66:67] op_sel_hi:[1,1,0]
	v_pk_fma_f32 v[54:55], v[42:43], v[54:55], v[74:75] op_sel_hi:[1,1,0]
	v_sub_f32_e32 v40, v68, v70
	v_sub_f32_e32 v44, v60, v62
	v_mov_b32_e32 v42, v56
	v_mov_b32_e32 v46, v64
	v_mov_b32_e32 v43, v54
	v_mov_b32_e32 v47, v52
.LBB0_1259:
	s_or_b64 exec, exec, s[4:5]
	v_ashrrev_i32_e32 v51, 31, v50
	v_lshlrev_b64 v[50:51], 11, v[50:51]
	v_pk_mul_f32 v[56:57], v[40:41], s[14:15] op_sel_hi:[1,0]
	v_pk_mul_f32 v[52:53], v[44:45], s[14:15] op_sel_hi:[1,0]
	v_pk_mul_f32 v[54:55], v[46:47], s[14:15] op_sel_hi:[1,0]
	v_pk_mul_f32 v[58:59], v[42:43], s[14:15] op_sel_hi:[1,0]
	v_cndmask_b32_e32 v56, v40, v56, vcc
	v_cndmask_b32_e32 v57, v41, v57, vcc
	v_lshl_add_u64 v[40:41], s[26:27], 0, v[50:51]
	v_cndmask_b32_e32 v49, v42, v58, vcc
	v_cndmask_b32_e32 v58, v43, v59, vcc
	v_cndmask_b32_e32 v43, v46, v54, vcc
	v_cndmask_b32_e32 v42, v44, v52, vcc
	v_cndmask_b32_e32 v44, v45, v53, vcc
	v_lshl_add_u64 v[40:41], v[40:41], 0, v[136:137]
	v_cndmask_b32_e32 v46, v47, v55, vcc
	v_cvt_pk_bf16_f32 v42, v42, v44
	v_cvt_pk_bf16_f32 v43, v43, v46
	v_cvt_pk_bf16_f32 v44, v56, v57
	v_cvt_pk_bf16_f32 v45, v49, v58
	global_store_dwordx4 v[40:41], v[42:45], off
	s_and_saveexec_b64 s[4:5], s[24:25]
	s_cbranch_execz .LBB0_1261
	v_mov_b32_e32 v49, v137
	v_mov_b64_e32 v[42:43], v[192:193]
	v_mov_b64_e32 v[44:45], v[194:195]
	v_mov_b64_e32 v[46:47], v[196:197]
	v_mov_b64_e32 v[48:49], v[198:199]
	v_pk_mul_f32 v[50:51], v[36:37], v[42:43]
	v_pk_mul_f32 v[52:53], v[36:37], v[46:47] op_sel:[1,0] op_sel_hi:[0,0]
	v_pk_mul_f32 v[60:61], v[32:33], v[48:49] op_sel:[1,0] op_sel_hi:[0,0]
	v_mov_b32_e32 v46, v43
	v_mul_f32_e32 v54, v39, v47
	v_mul_f32_e32 v56, v39, v43
	v_pk_mul_f32 v[58:59], v[32:33], v[44:45]
	v_mov_b32_e32 v48, v45
	v_mul_f32_e32 v62, v35, v49
	v_mul_f32_e32 v64, v35, v45
	v_pk_fma_f32 v[36:37], v[36:37], v[42:43], v[52:53] op_sel_hi:[1,0,1]
	v_mov_b32_e32 v42, v47
	v_pk_fma_f32 v[32:33], v[32:33], v[44:45], v[60:61] op_sel_hi:[1,0,1]
	v_mov_b32_e32 v44, v49
	v_pk_fma_f32 v[54:55], v[38:39], v[46:47], v[54:55] op_sel_hi:[1,1,0] neg_lo:[0,0,1] neg_hi:[0,0,1]
	v_pk_fma_f32 v[46:47], v[34:35], v[48:49], v[62:63] op_sel_hi:[1,1,0] neg_lo:[0,0,1] neg_hi:[0,0,1]
	v_pk_fma_f32 v[42:43], v[38:39], v[42:43], v[56:57] op_sel_hi:[1,1,0]
	v_pk_fma_f32 v[44:45], v[34:35], v[44:45], v[64:65] op_sel_hi:[1,1,0]
	v_sub_f32_e32 v32, v58, v60
	v_sub_f32_e32 v36, v50, v52
	v_mov_b32_e32 v34, v46
	v_mov_b32_e32 v38, v54
	v_mov_b32_e32 v35, v44
	v_mov_b32_e32 v39, v42
.LBB0_1261:
	s_or_b64 exec, exec, s[4:5]
	v_pk_mul_f32 v[42:43], v[36:37], s[14:15] op_sel_hi:[1,0]
	v_pk_mul_f32 v[44:45], v[38:39], s[14:15] op_sel_hi:[1,0]
	v_pk_mul_f32 v[46:47], v[32:33], s[14:15] op_sel_hi:[1,0]
	v_pk_mul_f32 v[48:49], v[34:35], s[14:15] op_sel_hi:[1,0]
	s_nop 0
	v_cndmask_b32_e32 v48, v34, v48, vcc
	v_cndmask_b32_e32 v34, v32, v46, vcc
	v_cndmask_b32_e32 v46, v33, v47, vcc
	v_cndmask_b32_e32 v33, v38, v44, vcc
	v_cndmask_b32_e32 v32, v36, v42, vcc
	v_cndmask_b32_e32 v35, v35, v49, vcc
	v_cndmask_b32_e32 v38, v39, v45, vcc
	v_cndmask_b32_e32 v36, v37, v43, vcc
	v_cvt_pk_bf16_f32 v32, v32, v36
	v_cvt_pk_bf16_f32 v33, v33, v38
	v_cvt_pk_bf16_f32 v34, v34, v46
	v_cvt_pk_bf16_f32 v35, v48, v35
	global_store_dwordx4 v[40:41], v[32:35], off offset:256
	s_nop 1
	v_add_u32_e32 v34, 0xa0, v150
	v_lshlrev_b32_e32 v32, 3, v34
	v_and_b32_e32 v32, 0xff78, v32
	v_lshlrev_b32_e32 v32, 2, v32
	s_and_saveexec_b64 s[4:5], s[24:25]
	s_cbranch_execz .LBB0_1263
	v_mov_b32_e32 v33, v137
	v_mov_b64_e32 v[36:37], v[200:201]
	v_mov_b64_e32 v[38:39], v[202:203]
	v_mov_b64_e32 v[40:41], v[204:205]
	v_mov_b64_e32 v[42:43], v[206:207]
	v_pk_mul_f32 v[44:45], v[28:29], v[36:37]
	v_pk_mul_f32 v[46:47], v[28:29], v[40:41] op_sel:[1,0] op_sel_hi:[0,0]
	v_pk_mul_f32 v[54:55], v[24:25], v[42:43] op_sel:[1,0] op_sel_hi:[0,0]
	v_mov_b32_e32 v40, v37
	v_mul_f32_e32 v48, v31, v41
	v_mul_f32_e32 v50, v31, v37
	v_pk_mul_f32 v[52:53], v[24:25], v[38:39]
	v_mov_b32_e32 v42, v39
	v_mul_f32_e32 v56, v27, v43
	v_mul_f32_e32 v58, v27, v39
	v_pk_fma_f32 v[28:29], v[28:29], v[36:37], v[46:47] op_sel_hi:[1,0,1]
	v_mov_b32_e32 v36, v41
	v_pk_fma_f32 v[24:25], v[24:25], v[38:39], v[54:55] op_sel_hi:[1,0,1]
	v_mov_b32_e32 v38, v43
	v_pk_fma_f32 v[48:49], v[30:31], v[40:41], v[48:49] op_sel_hi:[1,1,0] neg_lo:[0,0,1] neg_hi:[0,0,1]
	v_pk_fma_f32 v[40:41], v[26:27], v[42:43], v[56:57] op_sel_hi:[1,1,0] neg_lo:[0,0,1] neg_hi:[0,0,1]
	v_pk_fma_f32 v[36:37], v[30:31], v[36:37], v[50:51] op_sel_hi:[1,1,0]
	v_pk_fma_f32 v[38:39], v[26:27], v[38:39], v[58:59] op_sel_hi:[1,1,0]
	v_sub_f32_e32 v24, v52, v54
	v_sub_f32_e32 v28, v44, v46
	v_mov_b32_e32 v26, v40
	v_mov_b32_e32 v30, v48
	v_mov_b32_e32 v27, v38
	v_mov_b32_e32 v31, v36
.LBB0_1263:
	s_or_b64 exec, exec, s[4:5]
	v_ashrrev_i32_e32 v35, 31, v34
	v_lshlrev_b64 v[34:35], 11, v[34:35]
	v_pk_mul_f32 v[40:41], v[24:25], s[14:15] op_sel_hi:[1,0]
	v_pk_mul_f32 v[36:37], v[28:29], s[14:15] op_sel_hi:[1,0]
	v_pk_mul_f32 v[38:39], v[30:31], s[14:15] op_sel_hi:[1,0]
	v_pk_mul_f32 v[42:43], v[26:27], s[14:15] op_sel_hi:[1,0]
	v_cndmask_b32_e32 v40, v24, v40, vcc
	v_cndmask_b32_e32 v41, v25, v41, vcc
	v_lshl_add_u64 v[24:25], s[26:27], 0, v[34:35]
	v_cndmask_b32_e32 v33, v26, v42, vcc
	v_cndmask_b32_e32 v42, v27, v43, vcc
	v_cndmask_b32_e32 v27, v30, v38, vcc
	v_cndmask_b32_e32 v26, v28, v36, vcc
	v_cndmask_b32_e32 v28, v29, v37, vcc
	v_lshl_add_u64 v[24:25], v[24:25], 0, v[136:137]
	v_cndmask_b32_e32 v30, v31, v39, vcc
	v_cvt_pk_bf16_f32 v26, v26, v28
	v_cvt_pk_bf16_f32 v27, v27, v30
	v_cvt_pk_bf16_f32 v28, v40, v41
	v_cvt_pk_bf16_f32 v29, v33, v42
	global_store_dwordx4 v[24:25], v[26:29], off
	s_and_saveexec_b64 s[4:5], s[24:25]
	s_cbranch_execz .LBB0_1265
	v_mov_b32_e32 v33, v137
	v_mov_b64_e32 v[26:27], v[200:201]
	v_mov_b64_e32 v[28:29], v[202:203]
	v_mov_b64_e32 v[30:31], v[204:205]
	v_mov_b64_e32 v[32:33], v[206:207]
	v_pk_mul_f32 v[34:35], v[20:21], v[26:27]
	v_pk_mul_f32 v[36:37], v[20:21], v[30:31] op_sel:[1,0] op_sel_hi:[0,0]
	v_pk_mul_f32 v[44:45], v[16:17], v[32:33] op_sel:[1,0] op_sel_hi:[0,0]
	v_mov_b32_e32 v30, v27
	v_mul_f32_e32 v38, v23, v31
	v_mul_f32_e32 v40, v23, v27
	v_pk_mul_f32 v[42:43], v[16:17], v[28:29]
	v_mov_b32_e32 v32, v29
	v_mul_f32_e32 v46, v19, v33
	v_mul_f32_e32 v48, v19, v29
	v_pk_fma_f32 v[20:21], v[20:21], v[26:27], v[36:37] op_sel_hi:[1,0,1]
	v_mov_b32_e32 v26, v31
	v_pk_fma_f32 v[16:17], v[16:17], v[28:29], v[44:45] op_sel_hi:[1,0,1]
	v_mov_b32_e32 v28, v33
	v_pk_fma_f32 v[38:39], v[22:23], v[30:31], v[38:39] op_sel_hi:[1,1,0] neg_lo:[0,0,1] neg_hi:[0,0,1]
	v_pk_fma_f32 v[30:31], v[18:19], v[32:33], v[46:47] op_sel_hi:[1,1,0] neg_lo:[0,0,1] neg_hi:[0,0,1]
	v_pk_fma_f32 v[26:27], v[22:23], v[26:27], v[40:41] op_sel_hi:[1,1,0]
	v_pk_fma_f32 v[28:29], v[18:19], v[28:29], v[48:49] op_sel_hi:[1,1,0]
	v_sub_f32_e32 v16, v42, v44
	v_sub_f32_e32 v20, v34, v36
	v_mov_b32_e32 v18, v30
	v_mov_b32_e32 v22, v38
	v_mov_b32_e32 v19, v28
	v_mov_b32_e32 v23, v26
.LBB0_1265:
	s_or_b64 exec, exec, s[4:5]
	v_pk_mul_f32 v[26:27], v[20:21], s[14:15] op_sel_hi:[1,0]
	v_pk_mul_f32 v[28:29], v[22:23], s[14:15] op_sel_hi:[1,0]
	v_pk_mul_f32 v[30:31], v[16:17], s[14:15] op_sel_hi:[1,0]
	v_pk_mul_f32 v[32:33], v[18:19], s[14:15] op_sel_hi:[1,0]
	s_nop 0
	v_cndmask_b32_e32 v32, v18, v32, vcc
	v_cndmask_b32_e32 v18, v16, v30, vcc
	v_cndmask_b32_e32 v30, v17, v31, vcc
	v_cndmask_b32_e32 v17, v22, v28, vcc
	v_cndmask_b32_e32 v16, v20, v26, vcc
	v_cndmask_b32_e32 v19, v19, v33, vcc
	v_cndmask_b32_e32 v22, v23, v29, vcc
	v_cndmask_b32_e32 v20, v21, v27, vcc
	v_cvt_pk_bf16_f32 v16, v16, v20
	v_cvt_pk_bf16_f32 v17, v17, v22
	v_cvt_pk_bf16_f32 v18, v18, v30
	v_cvt_pk_bf16_f32 v19, v32, v19
	global_store_dwordx4 v[24:25], v[16:19], off offset:256
	s_nop 1
	v_add_u32_e32 v18, 0xb0, v150
	v_lshlrev_b32_e32 v16, 3, v18
	v_and_b32_e32 v16, 0xfff8, v16
	v_lshlrev_b32_e32 v16, 2, v16
	s_and_saveexec_b64 s[4:5], s[24:25]
	s_cbranch_execz .LBB0_1267
	v_mov_b32_e32 v17, v137
	v_mov_b64_e32 v[20:21], v[208:209]
	v_mov_b64_e32 v[22:23], v[210:211]
	v_mov_b64_e32 v[24:25], v[212:213]
	v_mov_b64_e32 v[26:27], v[214:215]
	v_pk_mul_f32 v[28:29], v[12:13], v[20:21]
	v_pk_mul_f32 v[30:31], v[12:13], v[24:25] op_sel:[1,0] op_sel_hi:[0,0]
	v_pk_mul_f32 v[38:39], v[8:9], v[26:27] op_sel:[1,0] op_sel_hi:[0,0]
	v_mov_b32_e32 v24, v21
	v_mul_f32_e32 v32, v15, v25
	v_mul_f32_e32 v34, v15, v21
	v_pk_mul_f32 v[36:37], v[8:9], v[22:23]
	v_mov_b32_e32 v26, v23
	v_mul_f32_e32 v40, v11, v27
	v_mul_f32_e32 v42, v11, v23
	v_pk_fma_f32 v[12:13], v[12:13], v[20:21], v[30:31] op_sel_hi:[1,0,1]
	v_mov_b32_e32 v20, v25
	v_pk_fma_f32 v[8:9], v[8:9], v[22:23], v[38:39] op_sel_hi:[1,0,1]
	v_mov_b32_e32 v22, v27
	v_pk_fma_f32 v[32:33], v[14:15], v[24:25], v[32:33] op_sel_hi:[1,1,0] neg_lo:[0,0,1] neg_hi:[0,0,1]
	v_pk_fma_f32 v[24:25], v[10:11], v[26:27], v[40:41] op_sel_hi:[1,1,0] neg_lo:[0,0,1] neg_hi:[0,0,1]
	v_pk_fma_f32 v[20:21], v[14:15], v[20:21], v[34:35] op_sel_hi:[1,1,0]
	v_pk_fma_f32 v[22:23], v[10:11], v[22:23], v[42:43] op_sel_hi:[1,1,0]
	v_sub_f32_e32 v8, v36, v38
	v_sub_f32_e32 v12, v28, v30
	v_mov_b32_e32 v10, v24
	v_mov_b32_e32 v14, v32
	v_mov_b32_e32 v11, v22
	v_mov_b32_e32 v15, v20
.LBB0_1267:
	s_or_b64 exec, exec, s[4:5]
	v_ashrrev_i32_e32 v19, 31, v18
	v_lshlrev_b64 v[18:19], 11, v[18:19]
	v_pk_mul_f32 v[24:25], v[8:9], s[14:15] op_sel_hi:[1,0]
	v_pk_mul_f32 v[20:21], v[12:13], s[14:15] op_sel_hi:[1,0]
	v_pk_mul_f32 v[22:23], v[14:15], s[14:15] op_sel_hi:[1,0]
	v_pk_mul_f32 v[26:27], v[10:11], s[14:15] op_sel_hi:[1,0]
	v_cndmask_b32_e32 v24, v8, v24, vcc
	v_cndmask_b32_e32 v25, v9, v25, vcc
	v_lshl_add_u64 v[8:9], s[26:27], 0, v[18:19]
	v_cndmask_b32_e32 v17, v10, v26, vcc
	v_cndmask_b32_e32 v26, v11, v27, vcc
	v_cndmask_b32_e32 v11, v14, v22, vcc
	v_cndmask_b32_e32 v10, v12, v20, vcc
	v_cndmask_b32_e32 v12, v13, v21, vcc
	v_lshl_add_u64 v[8:9], v[8:9], 0, v[136:137]
	v_cndmask_b32_e32 v14, v15, v23, vcc
	v_cvt_pk_bf16_f32 v10, v10, v12
	v_cvt_pk_bf16_f32 v11, v11, v14
	v_cvt_pk_bf16_f32 v12, v24, v25
	v_cvt_pk_bf16_f32 v13, v17, v26
	global_store_dwordx4 v[8:9], v[10:13], off
	s_and_saveexec_b64 s[4:5], s[24:25]
	s_cbranch_execz .LBB0_1269
	v_mov_b32_e32 v17, v137
	v_mov_b64_e32 v[10:11], v[208:209]
	v_mov_b64_e32 v[12:13], v[210:211]
	v_mov_b64_e32 v[14:15], v[212:213]
	v_mov_b64_e32 v[16:17], v[214:215]
	v_pk_mul_f32 v[18:19], v[4:5], v[10:11]
	v_pk_mul_f32 v[20:21], v[4:5], v[14:15] op_sel:[1,0] op_sel_hi:[0,0]
	v_pk_mul_f32 v[28:29], v[0:1], v[16:17] op_sel:[1,0] op_sel_hi:[0,0]
	v_mov_b32_e32 v14, v11
	v_mul_f32_e32 v22, v7, v15
	v_mul_f32_e32 v24, v7, v11
	v_pk_mul_f32 v[26:27], v[0:1], v[12:13]
	v_mov_b32_e32 v16, v13
	v_mul_f32_e32 v30, v3, v17
	v_mul_f32_e32 v32, v3, v13
	v_pk_fma_f32 v[4:5], v[4:5], v[10:11], v[20:21] op_sel_hi:[1,0,1]
	v_mov_b32_e32 v10, v15
	v_pk_fma_f32 v[0:1], v[0:1], v[12:13], v[28:29] op_sel_hi:[1,0,1]
	v_mov_b32_e32 v12, v17
	v_pk_fma_f32 v[22:23], v[6:7], v[14:15], v[22:23] op_sel_hi:[1,1,0] neg_lo:[0,0,1] neg_hi:[0,0,1]
	v_pk_fma_f32 v[14:15], v[2:3], v[16:17], v[30:31] op_sel_hi:[1,1,0] neg_lo:[0,0,1] neg_hi:[0,0,1]
	v_pk_fma_f32 v[10:11], v[6:7], v[10:11], v[24:25] op_sel_hi:[1,1,0]
	v_pk_fma_f32 v[12:13], v[2:3], v[12:13], v[32:33] op_sel_hi:[1,1,0]
	v_sub_f32_e32 v0, v26, v28
	v_sub_f32_e32 v4, v18, v20
	v_mov_b32_e32 v2, v14
	v_mov_b32_e32 v6, v22
	v_mov_b32_e32 v3, v12
	v_mov_b32_e32 v7, v10
